# v34 + redundant second s_nop 15 removed after the four fp8 GEMM K-loops (hazard padding re-derived)
# speedup vs baseline: 1.0039x; 1.0039x over previous
.LBB0_585:
	ds_read_b128 v[24:27], v189
	ds_read_b128 v[28:31], v189 offset:16
	ds_read_b128 v[16:19], v189 offset:2048
	ds_read_b128 v[20:23], v189 offset:2064
	ds_read_b128 v[8:11], v189 offset:16384
	ds_read_b128 v[12:15], v189 offset:16400
	ds_read_b128 v[0:3], v189 offset:18432
	ds_read_b128 v[4:7], v189 offset:18448
	s_add_u32 s23, s30, 0xfffe0080
	s_addc_u32 s34, s31, -1
	s_cmp_eq_u32 s64, 4
	s_cselect_b32 s37, s21, s34
	s_cselect_b32 s36, s53, s23
	s_cselect_b32 s35, s15, s63
	s_cselect_b32 s34, s54, s55
	s_add_i32 m0, s11, 0xc000
	ds_read_b128 v[176:179], v190
	ds_read_b128 v[180:183], v190 offset:16
	ds_read_b128 v[192:195], v190 offset:2048
	ds_read_b128 v[196:199], v190 offset:2064
	ds_read_b128 v[200:203], v190 offset:4096
	ds_read_b128 v[204:207], v190 offset:4112
	ds_read_b128 v[208:211], v190 offset:6144
	ds_read_b128 v[212:215], v190 offset:6160
	global_load_lds_dwordx4 v164, s[30:31]
	s_add_i32 m0, s11, 0xe000
	v_mov_b32_e32 v169, v165
	global_load_lds_dwordx4 v168, s[30:31]
	s_waitcnt vmcnt(8)
	s_waitcnt lgkmcnt(0)
	s_barrier
	s_setprio 1
	s_waitcnt lgkmcnt(0)
	v_mfma_f32_16x16x128_f8f6f4 v[156:159], v[24:31], v[176:183], v[156:159]
	v_mfma_f32_16x16x128_f8f6f4 v[148:151], v[16:23], v[176:183], v[148:151]
	v_mfma_f32_16x16x128_f8f6f4 v[140:143], v[24:31], v[192:199], v[140:143]
	v_mfma_f32_16x16x128_f8f6f4 v[132:135], v[16:23], v[192:199], v[132:135]
	v_mfma_f32_16x16x128_f8f6f4 v[124:127], v[24:31], v[200:207], v[124:127]
	v_mfma_f32_16x16x128_f8f6f4 v[116:119], v[16:23], v[200:207], v[116:119]
	v_mfma_f32_16x16x128_f8f6f4 v[108:111], v[24:31], v[208:215], v[108:111]
	v_mfma_f32_16x16x128_f8f6f4 v[100:103], v[16:23], v[208:215], v[100:103]
	s_setprio 0
	s_setprio 1
	v_mfma_f32_16x16x128_f8f6f4 v[152:155], v[8:15], v[176:183], v[152:155]
	v_mfma_f32_16x16x128_f8f6f4 v[144:147], v[0:7], v[176:183], v[144:147]
	v_mfma_f32_16x16x128_f8f6f4 v[136:139], v[8:15], v[192:199], v[136:139]
	v_mfma_f32_16x16x128_f8f6f4 v[128:131], v[0:7], v[192:199], v[128:131]
	v_mfma_f32_16x16x128_f8f6f4 v[120:123], v[8:15], v[200:207], v[120:123]
	v_mfma_f32_16x16x128_f8f6f4 v[112:115], v[0:7], v[200:207], v[112:115]
	v_mfma_f32_16x16x128_f8f6f4 v[104:107], v[8:15], v[208:215], v[104:107]
	v_mfma_f32_16x16x128_f8f6f4 v[96:99], v[0:7], v[208:215], v[96:99]
	s_setprio 0
	s_barrier
	s_mov_b32 m0, s13
	ds_read_b128 v[192:195], v190 offset:16384
	ds_read_b128 v[196:199], v190 offset:16400
	ds_read_b128 v[200:203], v190 offset:18432
	ds_read_b128 v[204:207], v190 offset:18448
	ds_read_b128 v[208:211], v190 offset:20480
	ds_read_b128 v[212:215], v190 offset:20496
	ds_read_b128 v[216:219], v190 offset:22528
	ds_read_b128 v[220:223], v190 offset:22544
	global_load_lds_dwordx4 v166, s[34:35]
	s_mov_b32 m0, s22
	s_add_u32 s86, s34, 0x20000
	global_load_lds_dwordx4 v170, s[34:35]
	s_addc_u32 s87, s35, 0
	s_mov_b32 m0, s29
	v_mov_b32_e32 v167, v165
	global_load_lds_dwordx4 v166, s[86:87]
	s_mov_b32 m0, s38
	v_mov_b32_e32 v171, v165
	global_load_lds_dwordx4 v170, s[86:87]
	s_waitcnt vmcnt(6)
	s_waitcnt lgkmcnt(0)
	s_barrier
	s_setprio 1
	s_waitcnt lgkmcnt(0)
	v_mfma_f32_16x16x128_f8f6f4 v[92:95], v[24:31], v[192:199], v[92:95]
	v_mfma_f32_16x16x128_f8f6f4 v[84:87], v[16:23], v[192:199], v[84:87]
	s_mov_b32 m0, s11
	v_lshl_add_u64 v[182:183], s[34:35], 0, v[166:167]
	v_mfma_f32_16x16x128_f8f6f4 v[76:79], v[24:31], v[200:207], v[76:79]
	global_load_lds_dwordx4 v164, s[36:37]
	v_mfma_f32_16x16x128_f8f6f4 v[68:71], v[16:23], v[200:207], v[68:71]
	v_mfma_f32_16x16x128_f8f6f4 v[60:63], v[24:31], v[208:215], v[60:63]
	v_mfma_f32_16x16x128_f8f6f4 v[52:55], v[16:23], v[208:215], v[52:55]
	v_mfma_f32_16x16x128_f8f6f4 v[44:47], v[24:31], v[216:223], v[44:47]
	v_mfma_f32_16x16x128_f8f6f4 v[36:39], v[16:23], v[216:223], v[36:39]
	s_mov_b32 m0, s39
	v_lshl_add_u64 v[180:181], s[34:35], 0, v[170:171]
	s_setprio 0
	s_setprio 1
	v_mfma_f32_16x16x128_f8f6f4 v[88:91], v[8:15], v[192:199], v[88:91]
	global_load_lds_dwordx4 v168, s[36:37]
	v_lshl_add_u64 v[178:179], s[36:37], 0, v[164:165]
	v_lshl_add_u64 v[176:177], s[36:37], 0, v[168:169]
	v_mfma_f32_16x16x128_f8f6f4 v[80:83], v[0:7], v[192:199], v[80:83]
	v_mfma_f32_16x16x128_f8f6f4 v[72:75], v[8:15], v[200:207], v[72:75]
	v_mfma_f32_16x16x128_f8f6f4 v[64:67], v[0:7], v[200:207], v[64:67]
	v_mfma_f32_16x16x128_f8f6f4 v[56:59], v[8:15], v[208:215], v[56:59]
	v_mfma_f32_16x16x128_f8f6f4 v[48:51], v[0:7], v[208:215], v[48:51]
	v_mfma_f32_16x16x128_f8f6f4 v[40:43], v[8:15], v[216:223], v[40:43]
	v_mfma_f32_16x16x128_f8f6f4 v[32:35], v[0:7], v[216:223], v[32:35]
	s_setprio 0
	s_barrier
	ds_read_b128 v[0:3], v189 offset:32768
	ds_read_b128 v[4:7], v189 offset:32784
	ds_read_b128 v[8:11], v189 offset:34816
	ds_read_b128 v[12:15], v189 offset:34832
	ds_read_b128 v[16:19], v189 offset:49152
	ds_read_b128 v[20:23], v189 offset:49168
	ds_read_b128 v[24:27], v189 offset:51200
	ds_read_b128 v[28:31], v189 offset:51216
	s_add_u32 s36, s36, 0x20000
	s_addc_u32 s37, s37, 0
	s_mov_b32 m0, s40
	ds_read_b128 v[192:195], v190 offset:32768
	ds_read_b128 v[196:199], v190 offset:32784
	ds_read_b128 v[200:203], v190 offset:34816
	ds_read_b128 v[204:207], v190 offset:34832
	ds_read_b128 v[208:211], v190 offset:36864
	ds_read_b128 v[212:215], v190 offset:36880
	ds_read_b128 v[216:219], v190 offset:38912
	ds_read_b128 v[220:223], v190 offset:38928
	global_load_lds_dwordx4 v164, s[36:37]
	s_mov_b32 m0, s41
	s_nop 0
	global_load_lds_dwordx4 v168, s[36:37]
	s_waitcnt vmcnt(8)
	s_waitcnt lgkmcnt(0)
	s_barrier
	s_setprio 1
	s_waitcnt lgkmcnt(0)
	v_mfma_f32_16x16x128_f8f6f4 v[156:159], v[0:7], v[192:199], v[156:159]
	v_mfma_f32_16x16x128_f8f6f4 v[148:151], v[8:15], v[192:199], v[148:151]
	v_mfma_f32_16x16x128_f8f6f4 v[140:143], v[0:7], v[200:207], v[140:143]
	v_mfma_f32_16x16x128_f8f6f4 v[132:135], v[8:15], v[200:207], v[132:135]
	v_mfma_f32_16x16x128_f8f6f4 v[124:127], v[0:7], v[208:215], v[124:127]
	v_mfma_f32_16x16x128_f8f6f4 v[116:119], v[8:15], v[208:215], v[116:119]
	v_mfma_f32_16x16x128_f8f6f4 v[108:111], v[0:7], v[216:223], v[108:111]
	v_mfma_f32_16x16x128_f8f6f4 v[100:103], v[8:15], v[216:223], v[100:103]
	s_setprio 0
	s_setprio 1
	v_mfma_f32_16x16x128_f8f6f4 v[152:155], v[16:23], v[192:199], v[152:155]
	v_mfma_f32_16x16x128_f8f6f4 v[144:147], v[24:31], v[192:199], v[144:147]
	v_mfma_f32_16x16x128_f8f6f4 v[136:139], v[16:23], v[200:207], v[136:139]
	v_mfma_f32_16x16x128_f8f6f4 v[128:131], v[24:31], v[200:207], v[128:131]
	v_mfma_f32_16x16x128_f8f6f4 v[120:123], v[16:23], v[208:215], v[120:123]
	v_mfma_f32_16x16x128_f8f6f4 v[112:115], v[24:31], v[208:215], v[112:115]
	v_mfma_f32_16x16x128_f8f6f4 v[104:107], v[16:23], v[216:223], v[104:107]
	v_mfma_f32_16x16x128_f8f6f4 v[96:99], v[24:31], v[216:223], v[96:99]
	s_setprio 0
	s_barrier
	s_mov_b32 m0, s43
	v_lshl_add_u64 v[182:183], v[182:183], 0, s[6:7]
	ds_read_b128 v[192:195], v190 offset:49152
	ds_read_b128 v[196:199], v190 offset:49168
	ds_read_b128 v[200:203], v190 offset:51200
	ds_read_b128 v[204:207], v190 offset:51216
	ds_read_b128 v[208:211], v190 offset:53248
	ds_read_b128 v[212:215], v190 offset:53264
	ds_read_b128 v[216:219], v190 offset:55296
	ds_read_b128 v[220:223], v190 offset:55312
	global_load_lds_dwordx4 v[182:183], off
	v_lshl_add_u64 v[180:181], v[180:181], 0, s[6:7]
	s_mov_b32 m0, s44
	s_add_u32 s34, s34, 0x20080
	global_load_lds_dwordx4 v[180:181], off
	s_addc_u32 s35, s35, 0
	s_mov_b32 m0, s48
	v_lshl_add_u64 v[178:179], v[178:179], 0, s[6:7]
	global_load_lds_dwordx4 v166, s[34:35]
	s_mov_b32 m0, s49
	v_lshl_add_u64 v[176:177], v[176:177], 0, s[6:7]
	global_load_lds_dwordx4 v170, s[34:35]
	s_waitcnt vmcnt(6)
	s_waitcnt lgkmcnt(0)
	s_barrier
	s_setprio 1
	s_waitcnt lgkmcnt(0)
	v_mfma_f32_16x16x128_f8f6f4 v[92:95], v[0:7], v[192:199], v[92:95]
	v_mfma_f32_16x16x128_f8f6f4 v[84:87], v[8:15], v[192:199], v[84:87]
	s_mov_b32 m0, s45
	v_mfma_f32_16x16x128_f8f6f4 v[76:79], v[0:7], v[200:207], v[76:79]
	global_load_lds_dwordx4 v[178:179], off
	v_mfma_f32_16x16x128_f8f6f4 v[68:71], v[8:15], v[200:207], v[68:71]
	v_mfma_f32_16x16x128_f8f6f4 v[60:63], v[0:7], v[208:215], v[60:63]
	v_mfma_f32_16x16x128_f8f6f4 v[52:55], v[8:15], v[208:215], v[52:55]
	v_mfma_f32_16x16x128_f8f6f4 v[44:47], v[0:7], v[216:223], v[44:47]
	v_mfma_f32_16x16x128_f8f6f4 v[36:39], v[8:15], v[216:223], v[36:39]
	s_mov_b32 m0, s47
	s_setprio 0
	s_setprio 1
	v_mfma_f32_16x16x128_f8f6f4 v[88:91], v[16:23], v[192:199], v[88:91]
	s_add_i32 s64, s64, 2
	global_load_lds_dwordx4 v[176:177], off
	v_mfma_f32_16x16x128_f8f6f4 v[80:83], v[24:31], v[192:199], v[80:83]
	s_add_u32 s30, s30, 0x100
	v_mfma_f32_16x16x128_f8f6f4 v[72:75], v[16:23], v[200:207], v[72:75]
	s_addc_u32 s31, s31, 0
	v_mfma_f32_16x16x128_f8f6f4 v[64:67], v[24:31], v[200:207], v[64:67]
	s_add_u32 s55, s55, 0x100
	v_mfma_f32_16x16x128_f8f6f4 v[56:59], v[16:23], v[208:215], v[56:59]
	s_addc_u32 s63, s63, 0
	v_mfma_f32_16x16x128_f8f6f4 v[48:51], v[24:31], v[208:215], v[48:51]
	s_cmp_gt_u32 s64, 5
	v_mfma_f32_16x16x128_f8f6f4 v[40:43], v[16:23], v[216:223], v[40:43]
	v_mfma_f32_16x16x128_f8f6f4 v[32:35], v[24:31], v[216:223], v[32:35]
	s_setprio 0
	s_barrier
	s_cbranch_scc0 .LBB0_585
	s_nop 15
	s_and_b64 vcc, exec, s[8:9]
	s_cbranch_vccz .LBB0_588
	s_barrier

.LBB0_662:
	ds_read_b128 v[24:27], v189
	ds_read_b128 v[28:31], v189 offset:16
	ds_read_b128 v[16:19], v189 offset:2048
	ds_read_b128 v[20:23], v189 offset:2064
	ds_read_b128 v[8:11], v189 offset:16384
	ds_read_b128 v[12:15], v189 offset:16400
	ds_read_b128 v[0:3], v189 offset:18432
	ds_read_b128 v[4:7], v189 offset:18448
	s_add_u32 s24, s20, 0xfffa8080
	s_addc_u32 s25, s21, -1
	s_cmp_eq_u32 s48, 18
	s_cselect_b32 s27, s1, s25
	s_cselect_b32 s26, s0, s24
	s_cselect_b32 s25, s15, s47
	s_cselect_b32 s24, s14, s45
	s_add_i32 m0, s3, 0xc000
	ds_read_b128 v[176:179], v190
	ds_read_b128 v[180:183], v190 offset:16
	ds_read_b128 v[192:195], v190 offset:2048
	ds_read_b128 v[196:199], v190 offset:2064
	ds_read_b128 v[200:203], v190 offset:4096
	ds_read_b128 v[204:207], v190 offset:4112
	ds_read_b128 v[208:211], v190 offset:6144
	ds_read_b128 v[212:215], v190 offset:6160
	global_load_lds_dwordx4 v164, s[20:21]
	s_add_i32 m0, s3, 0xe000
	v_mov_b32_e32 v169, v165
	global_load_lds_dwordx4 v168, s[20:21]
	s_waitcnt vmcnt(8)
	s_waitcnt lgkmcnt(0)
	s_barrier
	s_setprio 1
	s_waitcnt lgkmcnt(0)
	v_mfma_f32_16x16x128_f8f6f4 v[156:159], v[24:31], v[176:183], v[156:159]
	v_mfma_f32_16x16x128_f8f6f4 v[152:155], v[16:23], v[176:183], v[152:155]
	v_mfma_f32_16x16x128_f8f6f4 v[148:151], v[24:31], v[192:199], v[148:151]
	v_mfma_f32_16x16x128_f8f6f4 v[140:143], v[16:23], v[192:199], v[140:143]
	v_mfma_f32_16x16x128_f8f6f4 v[132:135], v[24:31], v[200:207], v[132:135]
	v_mfma_f32_16x16x128_f8f6f4 v[124:127], v[16:23], v[200:207], v[124:127]
	v_mfma_f32_16x16x128_f8f6f4 v[116:119], v[24:31], v[208:215], v[116:119]
	v_mfma_f32_16x16x128_f8f6f4 v[108:111], v[16:23], v[208:215], v[108:111]
	s_setprio 0
	s_setprio 1
	v_mfma_f32_16x16x128_f8f6f4 v[144:147], v[8:15], v[176:183], v[144:147]
	v_mfma_f32_16x16x128_f8f6f4 v[136:139], v[0:7], v[176:183], v[136:139]
	v_mfma_f32_16x16x128_f8f6f4 v[128:131], v[8:15], v[192:199], v[128:131]
	v_mfma_f32_16x16x128_f8f6f4 v[120:123], v[0:7], v[192:199], v[120:123]
	v_mfma_f32_16x16x128_f8f6f4 v[112:115], v[8:15], v[200:207], v[112:115]
	v_mfma_f32_16x16x128_f8f6f4 v[104:107], v[0:7], v[200:207], v[104:107]
	v_mfma_f32_16x16x128_f8f6f4 v[100:103], v[8:15], v[208:215], v[100:103]
	v_mfma_f32_16x16x128_f8f6f4 v[96:99], v[0:7], v[208:215], v[96:99]
	s_setprio 0
	s_barrier
	s_mov_b32 m0, s13
	ds_read_b128 v[192:195], v190 offset:16384
	ds_read_b128 v[196:199], v190 offset:16400
	ds_read_b128 v[200:203], v190 offset:18432
	ds_read_b128 v[204:207], v190 offset:18448
	ds_read_b128 v[208:211], v190 offset:20480
	ds_read_b128 v[212:215], v190 offset:20496
	ds_read_b128 v[216:219], v190 offset:22528
	ds_read_b128 v[220:223], v190 offset:22544
	global_load_lds_dwordx4 v166, s[24:25]
	s_mov_b32 m0, s22
	s_add_u32 s50, s24, 0x58000
	global_load_lds_dwordx4 v170, s[24:25]
	s_addc_u32 s51, s25, 0
	s_mov_b32 m0, s23
	v_mov_b32_e32 v167, v165
	global_load_lds_dwordx4 v166, s[50:51]
	s_mov_b32 m0, s28
	v_mov_b32_e32 v171, v165
	global_load_lds_dwordx4 v170, s[50:51]
	s_waitcnt vmcnt(6)
	s_waitcnt lgkmcnt(0)
	s_barrier
	s_setprio 1
	s_waitcnt lgkmcnt(0)
	v_mfma_f32_16x16x128_f8f6f4 v[92:95], v[24:31], v[192:199], v[92:95]
	v_mfma_f32_16x16x128_f8f6f4 v[88:91], v[16:23], v[192:199], v[88:91]
	s_mov_b32 m0, s3
	v_lshl_add_u64 v[182:183], s[24:25], 0, v[166:167]
	v_mfma_f32_16x16x128_f8f6f4 v[84:87], v[24:31], v[200:207], v[84:87]
	global_load_lds_dwordx4 v164, s[26:27]
	v_mfma_f32_16x16x128_f8f6f4 v[76:79], v[16:23], v[200:207], v[76:79]
	v_mfma_f32_16x16x128_f8f6f4 v[68:71], v[24:31], v[208:215], v[68:71]
	v_mfma_f32_16x16x128_f8f6f4 v[60:63], v[16:23], v[208:215], v[60:63]
	v_mfma_f32_16x16x128_f8f6f4 v[52:55], v[24:31], v[216:223], v[52:55]
	v_mfma_f32_16x16x128_f8f6f4 v[44:47], v[16:23], v[216:223], v[44:47]
	s_mov_b32 m0, s29
	v_lshl_add_u64 v[180:181], s[24:25], 0, v[170:171]
	s_setprio 0
	s_setprio 1
	v_mfma_f32_16x16x128_f8f6f4 v[80:83], v[8:15], v[192:199], v[80:83]
	global_load_lds_dwordx4 v168, s[26:27]
	v_lshl_add_u64 v[178:179], s[26:27], 0, v[164:165]
	v_lshl_add_u64 v[176:177], s[26:27], 0, v[168:169]
	v_mfma_f32_16x16x128_f8f6f4 v[72:75], v[0:7], v[192:199], v[72:75]
	v_mfma_f32_16x16x128_f8f6f4 v[64:67], v[8:15], v[200:207], v[64:67]
	v_mfma_f32_16x16x128_f8f6f4 v[56:59], v[0:7], v[200:207], v[56:59]
	v_mfma_f32_16x16x128_f8f6f4 v[48:51], v[8:15], v[208:215], v[48:51]
	v_mfma_f32_16x16x128_f8f6f4 v[40:43], v[0:7], v[208:215], v[40:43]
	v_mfma_f32_16x16x128_f8f6f4 v[36:39], v[8:15], v[216:223], v[36:39]
	v_mfma_f32_16x16x128_f8f6f4 v[32:35], v[0:7], v[216:223], v[32:35]
	s_setprio 0
	s_barrier
	ds_read_b128 v[0:3], v189 offset:32768
	ds_read_b128 v[4:7], v189 offset:32784
	ds_read_b128 v[8:11], v189 offset:34816
	ds_read_b128 v[12:15], v189 offset:34832
	ds_read_b128 v[16:19], v189 offset:49152
	ds_read_b128 v[20:23], v189 offset:49168
	ds_read_b128 v[24:27], v189 offset:51200
	ds_read_b128 v[28:31], v189 offset:51216
	s_add_u32 s26, s26, 0x58000
	s_addc_u32 s27, s27, 0
	s_mov_b32 m0, s30
	ds_read_b128 v[192:195], v190 offset:32768
	ds_read_b128 v[196:199], v190 offset:32784
	ds_read_b128 v[200:203], v190 offset:34816
	ds_read_b128 v[204:207], v190 offset:34832
	ds_read_b128 v[208:211], v190 offset:36864
	ds_read_b128 v[212:215], v190 offset:36880
	ds_read_b128 v[216:219], v190 offset:38912
	ds_read_b128 v[220:223], v190 offset:38928
	global_load_lds_dwordx4 v164, s[26:27]
	s_mov_b32 m0, s31
	s_nop 0
	global_load_lds_dwordx4 v168, s[26:27]
	s_waitcnt vmcnt(8)
	s_waitcnt lgkmcnt(0)
	s_barrier
	s_setprio 1
	s_waitcnt lgkmcnt(0)
	v_mfma_f32_16x16x128_f8f6f4 v[156:159], v[0:7], v[192:199], v[156:159]
	v_mfma_f32_16x16x128_f8f6f4 v[152:155], v[8:15], v[192:199], v[152:155]
	v_mfma_f32_16x16x128_f8f6f4 v[148:151], v[0:7], v[200:207], v[148:151]
	v_mfma_f32_16x16x128_f8f6f4 v[140:143], v[8:15], v[200:207], v[140:143]
	v_mfma_f32_16x16x128_f8f6f4 v[132:135], v[0:7], v[208:215], v[132:135]
	v_mfma_f32_16x16x128_f8f6f4 v[124:127], v[8:15], v[208:215], v[124:127]
	v_mfma_f32_16x16x128_f8f6f4 v[116:119], v[0:7], v[216:223], v[116:119]
	v_mfma_f32_16x16x128_f8f6f4 v[108:111], v[8:15], v[216:223], v[108:111]
	s_setprio 0
	s_setprio 1
	v_mfma_f32_16x16x128_f8f6f4 v[144:147], v[16:23], v[192:199], v[144:147]
	v_mfma_f32_16x16x128_f8f6f4 v[136:139], v[24:31], v[192:199], v[136:139]
	v_mfma_f32_16x16x128_f8f6f4 v[128:131], v[16:23], v[200:207], v[128:131]
	v_mfma_f32_16x16x128_f8f6f4 v[120:123], v[24:31], v[200:207], v[120:123]
	v_mfma_f32_16x16x128_f8f6f4 v[112:115], v[16:23], v[208:215], v[112:115]
	v_mfma_f32_16x16x128_f8f6f4 v[104:107], v[24:31], v[208:215], v[104:107]
	v_mfma_f32_16x16x128_f8f6f4 v[100:103], v[16:23], v[216:223], v[100:103]
	v_mfma_f32_16x16x128_f8f6f4 v[96:99], v[24:31], v[216:223], v[96:99]
	s_setprio 0
	s_barrier
	s_mov_b32 m0, s35
	v_lshl_add_u64 v[182:183], v[182:183], 0, s[8:9]
	ds_read_b128 v[192:195], v190 offset:49152
	ds_read_b128 v[196:199], v190 offset:49168
	ds_read_b128 v[200:203], v190 offset:51200
	ds_read_b128 v[204:207], v190 offset:51216
	ds_read_b128 v[208:211], v190 offset:53248
	ds_read_b128 v[212:215], v190 offset:53264
	ds_read_b128 v[216:219], v190 offset:55296
	ds_read_b128 v[220:223], v190 offset:55312
	global_load_lds_dwordx4 v[182:183], off
	v_lshl_add_u64 v[180:181], v[180:181], 0, s[8:9]
	s_mov_b32 m0, s36
	s_add_u32 s24, s24, 0x58080
	global_load_lds_dwordx4 v[180:181], off
	s_addc_u32 s25, s25, 0
	s_mov_b32 m0, s39
	v_lshl_add_u64 v[178:179], v[178:179], 0, s[8:9]
	global_load_lds_dwordx4 v166, s[24:25]
	s_mov_b32 m0, s40
	v_lshl_add_u64 v[176:177], v[176:177], 0, s[8:9]
	global_load_lds_dwordx4 v170, s[24:25]
	s_waitcnt vmcnt(6)
	s_waitcnt lgkmcnt(0)
	s_barrier
	s_setprio 1
	s_waitcnt lgkmcnt(0)
	v_mfma_f32_16x16x128_f8f6f4 v[92:95], v[0:7], v[192:199], v[92:95]
	v_mfma_f32_16x16x128_f8f6f4 v[88:91], v[8:15], v[192:199], v[88:91]
	s_mov_b32 m0, s37
	v_mfma_f32_16x16x128_f8f6f4 v[84:87], v[0:7], v[200:207], v[84:87]
	global_load_lds_dwordx4 v[178:179], off
	v_mfma_f32_16x16x128_f8f6f4 v[76:79], v[8:15], v[200:207], v[76:79]
	v_mfma_f32_16x16x128_f8f6f4 v[68:71], v[0:7], v[208:215], v[68:71]
	v_mfma_f32_16x16x128_f8f6f4 v[60:63], v[8:15], v[208:215], v[60:63]
	v_mfma_f32_16x16x128_f8f6f4 v[52:55], v[0:7], v[216:223], v[52:55]
	v_mfma_f32_16x16x128_f8f6f4 v[44:47], v[8:15], v[216:223], v[44:47]
	s_mov_b32 m0, s38
	s_setprio 0
	s_setprio 1
	v_mfma_f32_16x16x128_f8f6f4 v[80:83], v[16:23], v[192:199], v[80:83]
	s_add_i32 s48, s48, 2
	global_load_lds_dwordx4 v[176:177], off
	v_mfma_f32_16x16x128_f8f6f4 v[72:75], v[24:31], v[192:199], v[72:75]
	s_add_u32 s20, s20, 0x100
	v_mfma_f32_16x16x128_f8f6f4 v[64:67], v[16:23], v[200:207], v[64:67]
	s_addc_u32 s21, s21, 0
	v_mfma_f32_16x16x128_f8f6f4 v[56:59], v[24:31], v[200:207], v[56:59]
	s_add_u32 s45, s45, 0x100
	v_mfma_f32_16x16x128_f8f6f4 v[48:51], v[16:23], v[208:215], v[48:51]
	s_addc_u32 s47, s47, 0
	v_mfma_f32_16x16x128_f8f6f4 v[40:43], v[24:31], v[208:215], v[40:43]
	s_cmp_gt_u32 s48, 19
	v_mfma_f32_16x16x128_f8f6f4 v[36:39], v[16:23], v[216:223], v[36:39]
	v_mfma_f32_16x16x128_f8f6f4 v[32:35], v[24:31], v[216:223], v[32:35]
	s_setprio 0
	s_barrier
	s_cbranch_scc0 .LBB0_662
	s_nop 15
	s_and_b64 vcc, exec, s[10:11]
	s_cbranch_vccz .LBB0_665
	s_barrier

.LBB0_1272:
	ds_read_b128 v[24:27], v182
	ds_read_b128 v[28:31], v182 offset:16
	ds_read_b128 v[16:19], v182 offset:2048
	ds_read_b128 v[20:23], v182 offset:2064
	ds_read_b128 v[8:11], v182 offset:16384
	ds_read_b128 v[12:15], v182 offset:16400
	ds_read_b128 v[0:3], v182 offset:18432
	ds_read_b128 v[4:7], v182 offset:18448
	s_add_u32 s30, s28, 0xfffe0080
	s_addc_u32 s31, s29, -1
	s_cmp_eq_u32 s65, 4
	s_cselect_b32 s35, s15, s31
	s_cselect_b32 s34, s57, s30
	s_cselect_b32 s31, s17, s64
	s_cselect_b32 s30, s62, s63
	s_add_i32 m0, s25, 0xc000
	ds_read_b128 v[172:175], v183
	ds_read_b128 v[176:179], v183 offset:16
	ds_read_b128 v[188:191], v183 offset:2048
	ds_read_b128 v[192:195], v183 offset:2064
	ds_read_b128 v[196:199], v183 offset:4096
	ds_read_b128 v[200:203], v183 offset:4112
	ds_read_b128 v[204:207], v183 offset:6144
	ds_read_b128 v[208:211], v183 offset:6160
	global_load_lds_dwordx4 v164, s[28:29]
	s_add_i32 m0, s25, 0xe000
	v_mov_b32_e32 v167, v165
	global_load_lds_dwordx4 v166, s[28:29]
	s_waitcnt vmcnt(8)
	s_waitcnt lgkmcnt(0)
	s_barrier
	s_setprio 1
	s_waitcnt lgkmcnt(0)
	v_mfma_f32_16x16x128_f8f6f4 v[156:159], v[24:31], v[172:179], v[156:159]
	v_mfma_f32_16x16x128_f8f6f4 v[148:151], v[16:23], v[172:179], v[148:151]
	v_mfma_f32_16x16x128_f8f6f4 v[140:143], v[24:31], v[188:195], v[140:143]
	v_mfma_f32_16x16x128_f8f6f4 v[132:135], v[16:23], v[188:195], v[132:135]
	v_mfma_f32_16x16x128_f8f6f4 v[124:127], v[24:31], v[196:203], v[124:127]
	v_mfma_f32_16x16x128_f8f6f4 v[116:119], v[16:23], v[196:203], v[116:119]
	v_mfma_f32_16x16x128_f8f6f4 v[108:111], v[24:31], v[204:211], v[108:111]
	v_mfma_f32_16x16x128_f8f6f4 v[100:103], v[16:23], v[204:211], v[100:103]
	s_setprio 0
	s_setprio 1
	v_mfma_f32_16x16x128_f8f6f4 v[152:155], v[8:15], v[172:179], v[152:155]
	v_mfma_f32_16x16x128_f8f6f4 v[144:147], v[0:7], v[172:179], v[144:147]
	v_mfma_f32_16x16x128_f8f6f4 v[136:139], v[8:15], v[188:195], v[136:139]
	v_mfma_f32_16x16x128_f8f6f4 v[128:131], v[0:7], v[188:195], v[128:131]
	v_mfma_f32_16x16x128_f8f6f4 v[120:123], v[8:15], v[196:203], v[120:123]
	v_mfma_f32_16x16x128_f8f6f4 v[112:115], v[0:7], v[196:203], v[112:115]
	v_mfma_f32_16x16x128_f8f6f4 v[104:107], v[8:15], v[204:211], v[104:107]
	v_mfma_f32_16x16x128_f8f6f4 v[96:99], v[0:7], v[204:211], v[96:99]
	s_setprio 0
	s_barrier
	s_mov_b32 m0, s27
	ds_read_b128 v[188:191], v183 offset:16384
	ds_read_b128 v[192:195], v183 offset:16400
	ds_read_b128 v[196:199], v183 offset:18432
	ds_read_b128 v[200:203], v183 offset:18448
	ds_read_b128 v[204:207], v183 offset:20480
	ds_read_b128 v[208:211], v183 offset:20496
	ds_read_b128 v[212:215], v183 offset:22528
	ds_read_b128 v[216:219], v183 offset:22544
	global_load_lds_dwordx4 v162, s[30:31]
	s_mov_b32 m0, s36
	s_add_u32 s66, s30, 0x20000
	global_load_lds_dwordx4 v168, s[30:31]
	s_addc_u32 s67, s31, 0
	s_mov_b32 m0, s37
	v_mov_b32_e32 v163, v165
	global_load_lds_dwordx4 v162, s[66:67]
	s_mov_b32 m0, s38
	v_mov_b32_e32 v169, v165
	global_load_lds_dwordx4 v168, s[66:67]
	s_waitcnt vmcnt(6)
	s_waitcnt lgkmcnt(0)
	s_barrier
	s_setprio 1
	s_waitcnt lgkmcnt(0)
	v_mfma_f32_16x16x128_f8f6f4 v[92:95], v[24:31], v[188:195], v[92:95]
	v_mfma_f32_16x16x128_f8f6f4 v[84:87], v[16:23], v[188:195], v[84:87]
	s_mov_b32 m0, s25
	v_lshl_add_u64 v[178:179], s[30:31], 0, v[162:163]
	v_mfma_f32_16x16x128_f8f6f4 v[76:79], v[24:31], v[196:203], v[76:79]
	global_load_lds_dwordx4 v164, s[34:35]
	v_mfma_f32_16x16x128_f8f6f4 v[68:71], v[16:23], v[196:203], v[68:71]
	v_mfma_f32_16x16x128_f8f6f4 v[60:63], v[24:31], v[204:211], v[60:63]
	v_mfma_f32_16x16x128_f8f6f4 v[52:55], v[16:23], v[204:211], v[52:55]
	v_mfma_f32_16x16x128_f8f6f4 v[44:47], v[24:31], v[212:219], v[44:47]
	v_mfma_f32_16x16x128_f8f6f4 v[36:39], v[16:23], v[212:219], v[36:39]
	s_mov_b32 m0, s39
	v_lshl_add_u64 v[176:177], s[30:31], 0, v[168:169]
	s_setprio 0
	s_setprio 1
	v_mfma_f32_16x16x128_f8f6f4 v[88:91], v[8:15], v[188:195], v[88:91]
	global_load_lds_dwordx4 v166, s[34:35]
	v_lshl_add_u64 v[174:175], s[34:35], 0, v[164:165]
	v_lshl_add_u64 v[172:173], s[34:35], 0, v[166:167]
	v_mfma_f32_16x16x128_f8f6f4 v[80:83], v[0:7], v[188:195], v[80:83]
	v_mfma_f32_16x16x128_f8f6f4 v[72:75], v[8:15], v[196:203], v[72:75]
	v_mfma_f32_16x16x128_f8f6f4 v[64:67], v[0:7], v[196:203], v[64:67]
	v_mfma_f32_16x16x128_f8f6f4 v[56:59], v[8:15], v[204:211], v[56:59]
	v_mfma_f32_16x16x128_f8f6f4 v[48:51], v[0:7], v[204:211], v[48:51]
	v_mfma_f32_16x16x128_f8f6f4 v[40:43], v[8:15], v[212:219], v[40:43]
	v_mfma_f32_16x16x128_f8f6f4 v[32:35], v[0:7], v[212:219], v[32:35]
	s_setprio 0
	s_barrier
	ds_read_b128 v[0:3], v182 offset:32768
	ds_read_b128 v[4:7], v182 offset:32784
	ds_read_b128 v[8:11], v182 offset:34816
	ds_read_b128 v[12:15], v182 offset:34832
	ds_read_b128 v[16:19], v182 offset:49152
	ds_read_b128 v[20:23], v182 offset:49168
	ds_read_b128 v[24:27], v182 offset:51200
	ds_read_b128 v[28:31], v182 offset:51216
	s_add_u32 s34, s34, 0x20000
	s_addc_u32 s35, s35, 0
	s_mov_b32 m0, s40
	ds_read_b128 v[188:191], v183 offset:32768
	ds_read_b128 v[192:195], v183 offset:32784
	ds_read_b128 v[196:199], v183 offset:34816
	ds_read_b128 v[200:203], v183 offset:34832
	ds_read_b128 v[204:207], v183 offset:36864
	ds_read_b128 v[208:211], v183 offset:36880
	ds_read_b128 v[212:215], v183 offset:38912
	ds_read_b128 v[216:219], v183 offset:38928
	global_load_lds_dwordx4 v164, s[34:35]
	s_mov_b32 m0, s41
	s_nop 0
	global_load_lds_dwordx4 v166, s[34:35]
	s_waitcnt vmcnt(8)
	s_waitcnt lgkmcnt(0)
	s_barrier
	s_setprio 1
	s_waitcnt lgkmcnt(0)
	v_mfma_f32_16x16x128_f8f6f4 v[156:159], v[0:7], v[188:195], v[156:159]
	v_mfma_f32_16x16x128_f8f6f4 v[148:151], v[8:15], v[188:195], v[148:151]
	v_mfma_f32_16x16x128_f8f6f4 v[140:143], v[0:7], v[196:203], v[140:143]
	v_mfma_f32_16x16x128_f8f6f4 v[132:135], v[8:15], v[196:203], v[132:135]
	v_mfma_f32_16x16x128_f8f6f4 v[124:127], v[0:7], v[204:211], v[124:127]
	v_mfma_f32_16x16x128_f8f6f4 v[116:119], v[8:15], v[204:211], v[116:119]
	v_mfma_f32_16x16x128_f8f6f4 v[108:111], v[0:7], v[212:219], v[108:111]
	v_mfma_f32_16x16x128_f8f6f4 v[100:103], v[8:15], v[212:219], v[100:103]
	s_setprio 0
	s_setprio 1
	v_mfma_f32_16x16x128_f8f6f4 v[152:155], v[16:23], v[188:195], v[152:155]
	v_mfma_f32_16x16x128_f8f6f4 v[144:147], v[24:31], v[188:195], v[144:147]
	v_mfma_f32_16x16x128_f8f6f4 v[136:139], v[16:23], v[196:203], v[136:139]
	v_mfma_f32_16x16x128_f8f6f4 v[128:131], v[24:31], v[196:203], v[128:131]
	v_mfma_f32_16x16x128_f8f6f4 v[120:123], v[16:23], v[204:211], v[120:123]
	v_mfma_f32_16x16x128_f8f6f4 v[112:115], v[24:31], v[204:211], v[112:115]
	v_mfma_f32_16x16x128_f8f6f4 v[104:107], v[16:23], v[212:219], v[104:107]
	v_mfma_f32_16x16x128_f8f6f4 v[96:99], v[24:31], v[212:219], v[96:99]
	s_setprio 0
	s_barrier
	s_mov_b32 m0, s43
	v_lshl_add_u64 v[178:179], v[178:179], 0, s[6:7]
	ds_read_b128 v[188:191], v183 offset:49152
	ds_read_b128 v[192:195], v183 offset:49168
	ds_read_b128 v[196:199], v183 offset:51200
	ds_read_b128 v[200:203], v183 offset:51216
	ds_read_b128 v[204:207], v183 offset:53248
	ds_read_b128 v[208:211], v183 offset:53264
	ds_read_b128 v[212:215], v183 offset:55296
	ds_read_b128 v[216:219], v183 offset:55312
	global_load_lds_dwordx4 v[178:179], off
	v_lshl_add_u64 v[176:177], v[176:177], 0, s[6:7]
	s_mov_b32 m0, s44
	s_add_u32 s30, s30, 0x20080
	global_load_lds_dwordx4 v[176:177], off
	s_addc_u32 s31, s31, 0
	s_mov_b32 m0, s48
	v_lshl_add_u64 v[174:175], v[174:175], 0, s[6:7]
	global_load_lds_dwordx4 v162, s[30:31]
	s_mov_b32 m0, s49
	v_lshl_add_u64 v[172:173], v[172:173], 0, s[6:7]
	global_load_lds_dwordx4 v168, s[30:31]
	s_waitcnt vmcnt(6)
	s_waitcnt lgkmcnt(0)
	s_barrier
	s_setprio 1
	s_waitcnt lgkmcnt(0)
	v_mfma_f32_16x16x128_f8f6f4 v[92:95], v[0:7], v[188:195], v[92:95]
	v_mfma_f32_16x16x128_f8f6f4 v[84:87], v[8:15], v[188:195], v[84:87]
	s_mov_b32 m0, s45
	v_mfma_f32_16x16x128_f8f6f4 v[76:79], v[0:7], v[196:203], v[76:79]
	global_load_lds_dwordx4 v[174:175], off
	v_mfma_f32_16x16x128_f8f6f4 v[68:71], v[8:15], v[196:203], v[68:71]
	v_mfma_f32_16x16x128_f8f6f4 v[60:63], v[0:7], v[204:211], v[60:63]
	v_mfma_f32_16x16x128_f8f6f4 v[52:55], v[8:15], v[204:211], v[52:55]
	v_mfma_f32_16x16x128_f8f6f4 v[44:47], v[0:7], v[212:219], v[44:47]
	v_mfma_f32_16x16x128_f8f6f4 v[36:39], v[8:15], v[212:219], v[36:39]
	s_mov_b32 m0, s47
	s_setprio 0
	s_setprio 1
	v_mfma_f32_16x16x128_f8f6f4 v[88:91], v[16:23], v[188:195], v[88:91]
	s_add_i32 s65, s65, 2
	global_load_lds_dwordx4 v[172:173], off
	v_mfma_f32_16x16x128_f8f6f4 v[80:83], v[24:31], v[188:195], v[80:83]
	s_add_u32 s28, s28, 0x100
	v_mfma_f32_16x16x128_f8f6f4 v[72:75], v[16:23], v[196:203], v[72:75]
	s_addc_u32 s29, s29, 0
	v_mfma_f32_16x16x128_f8f6f4 v[64:67], v[24:31], v[196:203], v[64:67]
	s_add_u32 s63, s63, 0x100
	v_mfma_f32_16x16x128_f8f6f4 v[56:59], v[16:23], v[204:211], v[56:59]
	s_addc_u32 s64, s64, 0
	v_mfma_f32_16x16x128_f8f6f4 v[48:51], v[24:31], v[204:211], v[48:51]
	s_cmp_gt_u32 s65, 5
	v_mfma_f32_16x16x128_f8f6f4 v[40:43], v[16:23], v[212:219], v[40:43]
	v_mfma_f32_16x16x128_f8f6f4 v[32:35], v[24:31], v[212:219], v[32:35]
	s_setprio 0
	s_barrier
	s_cbranch_scc0 .LBB0_1272
	s_nop 15
	s_and_b64 vcc, exec, s[8:9]
	s_cbranch_vccz .LBB0_1275
	s_barrier

.LBB0_1349:
	ds_read_b128 v[24:27], v181
	ds_read_b128 v[28:31], v181 offset:16
	ds_read_b128 v[16:19], v181 offset:2048
	ds_read_b128 v[20:23], v181 offset:2064
	ds_read_b128 v[8:11], v181 offset:16384
	ds_read_b128 v[12:15], v181 offset:16400
	ds_read_b128 v[0:3], v181 offset:18432
	ds_read_b128 v[4:7], v181 offset:18448
	s_add_u32 s34, s30, 0xfff90080
	s_addc_u32 s35, s31, -1
	s_cmp_eq_u32 s74, 24
	s_cselect_b32 s37, s1, s35
	s_cselect_b32 s36, s0, s34
	s_cselect_b32 s35, s27, s73
	s_cselect_b32 s34, s26, s72
	s_add_i32 m0, s29, 0xc000
	ds_read_b128 v[172:175], v182
	ds_read_b128 v[176:179], v182 offset:16
	ds_read_b128 v[188:191], v182 offset:2048
	ds_read_b128 v[192:195], v182 offset:2064
	ds_read_b128 v[196:199], v182 offset:4096
	ds_read_b128 v[200:203], v182 offset:4112
	ds_read_b128 v[204:207], v182 offset:6144
	ds_read_b128 v[208:211], v182 offset:6160
	global_load_lds_dwordx4 v162, s[30:31]
	s_add_i32 m0, s29, 0xe000
	v_mov_b32_e32 v167, v163
	global_load_lds_dwordx4 v166, s[30:31]
	s_waitcnt vmcnt(8)
	s_waitcnt lgkmcnt(0)
	s_barrier
	s_setprio 1
	s_waitcnt lgkmcnt(0)
	v_mfma_f32_16x16x128_f8f6f4 v[156:159], v[24:31], v[172:179], v[156:159]
	v_mfma_f32_16x16x128_f8f6f4 v[152:155], v[16:23], v[172:179], v[152:155]
	v_mfma_f32_16x16x128_f8f6f4 v[148:151], v[24:31], v[188:195], v[148:151]
	v_mfma_f32_16x16x128_f8f6f4 v[140:143], v[16:23], v[188:195], v[140:143]
	v_mfma_f32_16x16x128_f8f6f4 v[132:135], v[24:31], v[196:203], v[132:135]
	v_mfma_f32_16x16x128_f8f6f4 v[124:127], v[16:23], v[196:203], v[124:127]
	v_mfma_f32_16x16x128_f8f6f4 v[116:119], v[24:31], v[204:211], v[116:119]
	v_mfma_f32_16x16x128_f8f6f4 v[108:111], v[16:23], v[204:211], v[108:111]
	s_setprio 0
	s_setprio 1
	v_mfma_f32_16x16x128_f8f6f4 v[144:147], v[8:15], v[172:179], v[144:147]
	v_mfma_f32_16x16x128_f8f6f4 v[136:139], v[0:7], v[172:179], v[136:139]
	v_mfma_f32_16x16x128_f8f6f4 v[128:131], v[8:15], v[188:195], v[128:131]
	v_mfma_f32_16x16x128_f8f6f4 v[120:123], v[0:7], v[188:195], v[120:123]
	v_mfma_f32_16x16x128_f8f6f4 v[112:115], v[8:15], v[196:203], v[112:115]
	v_mfma_f32_16x16x128_f8f6f4 v[104:107], v[0:7], v[196:203], v[104:107]
	v_mfma_f32_16x16x128_f8f6f4 v[100:103], v[8:15], v[204:211], v[100:103]
	v_mfma_f32_16x16x128_f8f6f4 v[96:99], v[0:7], v[204:211], v[96:99]
	s_setprio 0
	s_barrier
	s_mov_b32 m0, s39
	ds_read_b128 v[188:191], v182 offset:16384
	ds_read_b128 v[192:195], v182 offset:16400
	ds_read_b128 v[196:199], v182 offset:18432
	ds_read_b128 v[200:203], v182 offset:18448
	ds_read_b128 v[204:207], v182 offset:20480
	ds_read_b128 v[208:211], v182 offset:20496
	ds_read_b128 v[212:215], v182 offset:22528
	ds_read_b128 v[216:219], v182 offset:22544
	global_load_lds_dwordx4 v164, s[34:35]
	s_mov_b32 m0, s40
	s_add_u32 s76, s34, 0x70000
	global_load_lds_dwordx4 v168, s[34:35]
	s_addc_u32 s77, s35, 0
	s_mov_b32 m0, s41
	v_mov_b32_e32 v165, v163
	global_load_lds_dwordx4 v164, s[76:77]
	s_mov_b32 m0, s42
	v_mov_b32_e32 v169, v163
	global_load_lds_dwordx4 v168, s[76:77]
	s_waitcnt vmcnt(6)
	s_waitcnt lgkmcnt(0)
	s_barrier
	s_setprio 1
	s_waitcnt lgkmcnt(0)
	v_mfma_f32_16x16x128_f8f6f4 v[92:95], v[24:31], v[188:195], v[92:95]
	v_mfma_f32_16x16x128_f8f6f4 v[88:91], v[16:23], v[188:195], v[88:91]
	s_mov_b32 m0, s29
	v_lshl_add_u64 v[178:179], s[34:35], 0, v[164:165]
	v_mfma_f32_16x16x128_f8f6f4 v[84:87], v[24:31], v[196:203], v[84:87]
	global_load_lds_dwordx4 v162, s[36:37]
	v_mfma_f32_16x16x128_f8f6f4 v[76:79], v[16:23], v[196:203], v[76:79]
	v_mfma_f32_16x16x128_f8f6f4 v[68:71], v[24:31], v[204:211], v[68:71]
	v_mfma_f32_16x16x128_f8f6f4 v[60:63], v[16:23], v[204:211], v[60:63]
	v_mfma_f32_16x16x128_f8f6f4 v[52:55], v[24:31], v[212:219], v[52:55]
	v_mfma_f32_16x16x128_f8f6f4 v[44:47], v[16:23], v[212:219], v[44:47]
	s_mov_b32 m0, s43
	v_lshl_add_u64 v[176:177], s[34:35], 0, v[168:169]
	s_setprio 0
	s_setprio 1
	v_mfma_f32_16x16x128_f8f6f4 v[80:83], v[8:15], v[188:195], v[80:83]
	global_load_lds_dwordx4 v166, s[36:37]
	v_lshl_add_u64 v[174:175], s[36:37], 0, v[162:163]
	v_lshl_add_u64 v[172:173], s[36:37], 0, v[166:167]
	v_mfma_f32_16x16x128_f8f6f4 v[72:75], v[0:7], v[188:195], v[72:75]
	v_mfma_f32_16x16x128_f8f6f4 v[64:67], v[8:15], v[196:203], v[64:67]
	v_mfma_f32_16x16x128_f8f6f4 v[56:59], v[0:7], v[196:203], v[56:59]
	v_mfma_f32_16x16x128_f8f6f4 v[48:51], v[8:15], v[204:211], v[48:51]
	v_mfma_f32_16x16x128_f8f6f4 v[40:43], v[0:7], v[204:211], v[40:43]
	v_mfma_f32_16x16x128_f8f6f4 v[36:39], v[8:15], v[212:219], v[36:39]
	v_mfma_f32_16x16x128_f8f6f4 v[32:35], v[0:7], v[212:219], v[32:35]
	s_setprio 0
	s_barrier
	ds_read_b128 v[0:3], v181 offset:32768
	ds_read_b128 v[4:7], v181 offset:32784
	ds_read_b128 v[8:11], v181 offset:34816
	ds_read_b128 v[12:15], v181 offset:34832
	ds_read_b128 v[16:19], v181 offset:49152
	ds_read_b128 v[20:23], v181 offset:49168
	ds_read_b128 v[24:27], v181 offset:51200
	ds_read_b128 v[28:31], v181 offset:51216
	s_add_u32 s36, s36, 0x70000
	s_addc_u32 s37, s37, 0
	s_mov_b32 m0, s44
	ds_read_b128 v[188:191], v182 offset:32768
	ds_read_b128 v[192:195], v182 offset:32784
	ds_read_b128 v[196:199], v182 offset:34816
	ds_read_b128 v[200:203], v182 offset:34832
	ds_read_b128 v[204:207], v182 offset:36864
	ds_read_b128 v[208:211], v182 offset:36880
	ds_read_b128 v[212:215], v182 offset:38912
	ds_read_b128 v[216:219], v182 offset:38928
	global_load_lds_dwordx4 v162, s[36:37]
	s_mov_b32 m0, s45
	s_nop 0
	global_load_lds_dwordx4 v166, s[36:37]
	s_waitcnt vmcnt(8)
	s_waitcnt lgkmcnt(0)
	s_barrier
	s_setprio 1
	s_waitcnt lgkmcnt(0)
	v_mfma_f32_16x16x128_f8f6f4 v[156:159], v[0:7], v[188:195], v[156:159]
	v_mfma_f32_16x16x128_f8f6f4 v[152:155], v[8:15], v[188:195], v[152:155]
	v_mfma_f32_16x16x128_f8f6f4 v[148:151], v[0:7], v[196:203], v[148:151]
	v_mfma_f32_16x16x128_f8f6f4 v[140:143], v[8:15], v[196:203], v[140:143]
	v_mfma_f32_16x16x128_f8f6f4 v[132:135], v[0:7], v[204:211], v[132:135]
	v_mfma_f32_16x16x128_f8f6f4 v[124:127], v[8:15], v[204:211], v[124:127]
	v_mfma_f32_16x16x128_f8f6f4 v[116:119], v[0:7], v[212:219], v[116:119]
	v_mfma_f32_16x16x128_f8f6f4 v[108:111], v[8:15], v[212:219], v[108:111]
	s_setprio 0
	s_setprio 1
	v_mfma_f32_16x16x128_f8f6f4 v[144:147], v[16:23], v[188:195], v[144:147]
	v_mfma_f32_16x16x128_f8f6f4 v[136:139], v[24:31], v[188:195], v[136:139]
	v_mfma_f32_16x16x128_f8f6f4 v[128:131], v[16:23], v[196:203], v[128:131]
	v_mfma_f32_16x16x128_f8f6f4 v[120:123], v[24:31], v[196:203], v[120:123]
	v_mfma_f32_16x16x128_f8f6f4 v[112:115], v[16:23], v[204:211], v[112:115]
	v_mfma_f32_16x16x128_f8f6f4 v[104:107], v[24:31], v[204:211], v[104:107]
	v_mfma_f32_16x16x128_f8f6f4 v[100:103], v[16:23], v[212:219], v[100:103]
	v_mfma_f32_16x16x128_f8f6f4 v[96:99], v[24:31], v[212:219], v[96:99]
	s_setprio 0
	s_barrier
	s_mov_b32 m0, s48
	v_lshl_add_u64 v[178:179], v[178:179], 0, s[8:9]
	ds_read_b128 v[188:191], v182 offset:49152
	ds_read_b128 v[192:195], v182 offset:49168
	ds_read_b128 v[196:199], v182 offset:51200
	ds_read_b128 v[200:203], v182 offset:51216
	ds_read_b128 v[204:207], v182 offset:53248
	ds_read_b128 v[208:211], v182 offset:53264
	ds_read_b128 v[212:215], v182 offset:55296
	ds_read_b128 v[216:219], v182 offset:55312
	global_load_lds_dwordx4 v[178:179], off
	v_lshl_add_u64 v[176:177], v[176:177], 0, s[8:9]
	s_mov_b32 m0, s49
	s_add_u32 s34, s34, 0x70080
	global_load_lds_dwordx4 v[176:177], off
	s_addc_u32 s35, s35, 0
	s_mov_b32 m0, s57
	v_lshl_add_u64 v[174:175], v[174:175], 0, s[8:9]
	global_load_lds_dwordx4 v164, s[34:35]
	s_mov_b32 m0, s62
	v_lshl_add_u64 v[172:173], v[172:173], 0, s[8:9]
	global_load_lds_dwordx4 v168, s[34:35]
	s_waitcnt vmcnt(6)
	s_waitcnt lgkmcnt(0)
	s_barrier
	s_setprio 1
	s_waitcnt lgkmcnt(0)
	v_mfma_f32_16x16x128_f8f6f4 v[92:95], v[0:7], v[188:195], v[92:95]
	v_mfma_f32_16x16x128_f8f6f4 v[88:91], v[8:15], v[188:195], v[88:91]
	s_mov_b32 m0, s52
	v_mfma_f32_16x16x128_f8f6f4 v[84:87], v[0:7], v[196:203], v[84:87]
	global_load_lds_dwordx4 v[174:175], off
	v_mfma_f32_16x16x128_f8f6f4 v[76:79], v[8:15], v[196:203], v[76:79]
	v_mfma_f32_16x16x128_f8f6f4 v[68:71], v[0:7], v[204:211], v[68:71]
	v_mfma_f32_16x16x128_f8f6f4 v[60:63], v[8:15], v[204:211], v[60:63]
	v_mfma_f32_16x16x128_f8f6f4 v[52:55], v[0:7], v[212:219], v[52:55]
	v_mfma_f32_16x16x128_f8f6f4 v[44:47], v[8:15], v[212:219], v[44:47]
	s_mov_b32 m0, s53
	s_setprio 0
	s_setprio 1
	v_mfma_f32_16x16x128_f8f6f4 v[80:83], v[16:23], v[188:195], v[80:83]
	s_add_i32 s74, s74, 2
	global_load_lds_dwordx4 v[172:173], off
	v_mfma_f32_16x16x128_f8f6f4 v[72:75], v[24:31], v[188:195], v[72:75]
	s_add_u32 s30, s30, 0x100
	v_mfma_f32_16x16x128_f8f6f4 v[64:67], v[16:23], v[196:203], v[64:67]
	s_addc_u32 s31, s31, 0
	v_mfma_f32_16x16x128_f8f6f4 v[56:59], v[24:31], v[196:203], v[56:59]
	s_add_u32 s72, s72, 0x100
	v_mfma_f32_16x16x128_f8f6f4 v[48:51], v[16:23], v[204:211], v[48:51]
	s_addc_u32 s73, s73, 0
	v_mfma_f32_16x16x128_f8f6f4 v[40:43], v[24:31], v[204:211], v[40:43]
	s_cmp_gt_u32 s74, 25
	v_mfma_f32_16x16x128_f8f6f4 v[36:39], v[16:23], v[212:219], v[36:39]
	v_mfma_f32_16x16x128_f8f6f4 v[32:35], v[24:31], v[212:219], v[32:35]
	s_setprio 0
	s_barrier
	s_cbranch_scc0 .LBB0_1349
	s_nop 15
	s_and_b64 vcc, exec, s[10:11]
	s_cbranch_vccz .LBB0_1352
	s_barrier
